# P6 gate epilogue: fold -log2e into the per-row rstd once (rs'=rs*-log2e after v_rsq), drop 113 of 128 per-element v_mul per wave
# speedup vs baseline: 1.0031x; 1.0031x over previous
.LBB0_1310:
	s_lshl_b32 s0, s24, 8
	s_lshl_b32 s1, s60, 6
	s_add_i32 s1, s1, s0
	v_or_b32_e32 v130, s1, v195
	v_mov_b32_e32 v203, v1
	v_lshl_add_u64 v[132:133], s[28:29], 0, v[202:203]
	s_mov_b64 s[0:1], 0xa680000
	v_ashrrev_i32_e32 v131, 31, v130
	v_lshl_add_u64 v[132:133], v[132:133], 0, s[0:1]
	v_lshlrev_b64 v[134:135], 6, v[130:131]
	v_lshl_add_u64 v[134:135], v[132:133], 0, v[134:135]
	global_load_dwordx4 v[142:145], v[134:135], off
	v_or_b32_e32 v136, 16, v130
	v_ashrrev_i32_e32 v137, 31, v136
	v_lshlrev_b64 v[136:137], 6, v[136:137]
	v_lshl_add_u64 v[136:137], v[132:133], 0, v[136:137]
	global_load_dwordx4 v[146:149], v[136:137], off
	v_or_b32_e32 v136, 32, v130
	v_or_b32_e32 v130, 48, v130
	v_ashrrev_i32_e32 v131, 31, v130
	v_ashrrev_i32_e32 v137, 31, v136
	v_lshlrev_b64 v[130:131], 6, v[130:131]
	v_lshlrev_b64 v[136:137], 6, v[136:137]
	v_lshl_add_u64 v[130:131], v[132:133], 0, v[130:131]
	s_movk_i32 s1, 0x2000
	v_lshl_add_u64 v[136:137], v[132:133], 0, v[136:137]
	global_load_dwordx4 v[156:159], v[130:131], off
	v_add_co_u32_e32 v130, vcc, s1, v134
	global_load_dwordx4 v[152:155], v[136:137], off
	s_nop 0
	v_addc_co_u32_e32 v131, vcc, 0, v135, vcc
	global_load_dwordx4 v[160:163], v[130:131], off
	global_load_dwordx4 v[138:141], v[130:131], off offset:1024
	global_load_dwordx4 v[134:137], v[130:131], off offset:2048
	s_nop 0
	global_load_dwordx4 v[130:133], v[130:131], off offset:3072
	v_ashrrev_i32_e32 v201, 31, v200
	s_mov_b32 s0, 0x8000
	s_movk_i32 s84, 0x2000
	s_waitcnt vmcnt(0)
	v_mov_b32_e32 v150, v143
	v_mov_b32_e32 v151, v144
	v_mov_b32_e32 v143, v145
	v_pk_add_f32 v[142:143], v[150:151], v[142:143]
	s_nop 0
	v_add_f32_e32 v142, v142, v143
	ds_swizzle_b32 v143, v142 offset:swizzle(SWAP,16)
	s_waitcnt lgkmcnt(0)
	v_add_f32_e32 v142, v142, v143
	v_mov_b32_e32 v143, v142
	s_nop 1
	v_permlane32_swap_b32_e32 v142, v143
	v_add_f32_e32 v142, v142, v143
	v_fmamk_f32 v142, v142, 0x3a800000, v254
	v_rsq_f32_e32 v150, v142
	s_nop 0
	v_mul_f32_e32 v150, 0xbfb8aa3b, v150
	v_mov_b32_e32 v142, v147
	v_mov_b32_e32 v143, v148
	v_mov_b32_e32 v147, v149
	v_pk_add_f32 v[142:143], v[142:143], v[146:147]
	v_pk_mul_f32 v[124:125], v[124:125], v[150:151] op_sel_hi:[1,0]
	v_add_f32_e32 v142, v142, v143
	ds_swizzle_b32 v143, v142 offset:swizzle(SWAP,16)
	v_exp_f32_e32 v124, v124
	v_pk_mul_f32 v[128:129], v[128:129], v[150:151] op_sel_hi:[1,0]
	v_pk_mul_f32 v[126:127], v[126:127], v[150:151] op_sel_hi:[1,0]
	s_waitcnt lgkmcnt(0)
	v_add_f32_e32 v142, v142, v143
	v_mov_b32_e32 v143, v142
	s_nop 1
	v_permlane32_swap_b32_e32 v142, v143
	v_add_f32_e32 v142, v142, v143
	v_fmamk_f32 v142, v142, 0x3a800000, v254
	v_rsq_f32_e32 v148, v142
	s_nop 0
	v_mul_f32_e32 v148, 0xbfb8aa3b, v148
	v_mov_b32_e32 v142, v153
	v_mov_b32_e32 v143, v154
	v_mov_b32_e32 v153, v155
	v_pk_add_f32 v[142:143], v[142:143], v[152:153]
	v_mov_b32_e32 v152, v139
	v_mov_b32_e32 v153, v140
	v_mov_b32_e32 v139, v141
	v_mov_b32_e32 v140, v135
	v_mov_b32_e32 v141, v136
	v_mov_b32_e32 v135, v137
	v_mov_b32_e32 v136, v131
	v_mov_b32_e32 v137, v132
	v_mov_b32_e32 v131, v133
	v_pk_add_f32 v[130:131], v[136:137], v[130:131]
	v_add_f32_e32 v124, 1.0, v124
	v_add_f32_e32 v130, v130, v131
	ds_swizzle_b32 v131, v130 offset:swizzle(SWAP,16)
	v_pk_mul_f32 v[122:123], v[122:123], v[150:151] op_sel_hi:[1,0]
	s_waitcnt lgkmcnt(0)
	v_add_f32_e32 v130, v130, v131
	v_mov_b32_e32 v131, v130
	s_nop 1
	v_permlane32_swap_b32_e32 v130, v131
	v_add_f32_e32 v130, v130, v131
	v_rcp_f32_e32 v131, v124
	v_exp_f32_e32 v124, v129
	v_exp_f32_e32 v126, v126
	v_add_f32_e32 v124, 1.0, v124
	v_rcp_f32_e32 v129, v124
	v_exp_f32_e32 v122, v122
	v_exp_f32_e32 v127, v127
	v_exp_f32_e32 v123, v123
	v_exp_f32_e32 v128, v128
	v_exp_f32_e32 v124, v125
	v_pk_mul_f32 v[114:115], v[114:115], v[150:151] op_sel_hi:[1,0]
	v_add_f32_e32 v126, 1.0, v126
	v_add_f32_e32 v122, 1.0, v122
	v_add_f32_e32 v127, 1.0, v127
	v_add_f32_e32 v123, 1.0, v123
	v_add_f32_e32 v128, 1.0, v128
	v_add_f32_e32 v124, 1.0, v124
	v_pk_mul_f32 v[116:117], v[116:117], v[150:151] op_sel_hi:[1,0]
	v_rcp_f32_e32 v126, v126
	v_rcp_f32_e32 v122, v122
	v_rcp_f32_e32 v127, v127
	v_rcp_f32_e32 v123, v123
	v_rcp_f32_e32 v128, v128
	v_rcp_f32_e32 v132, v124
	v_exp_f32_e32 v114, v114
	v_exp_f32_e32 v115, v115
	v_exp_f32_e32 v116, v116
	v_cvt_pk_bf16_f32 v124, v126, v127
	v_cvt_pk_bf16_f32 v125, v128, v129
	v_cvt_pk_bf16_f32 v126, v122, v123
	v_cvt_pk_bf16_f32 v127, v131, v132
	v_lshl_add_u64 v[122:123], v[200:201], 4, s[26:27]
	v_pk_mul_f32 v[118:119], v[118:119], v[150:151] op_sel_hi:[1,0]
	v_add_f32_e32 v114, 1.0, v114
	global_store_dwordx4 v[122:123], v[124:127], off
	v_pk_mul_f32 v[120:121], v[120:121], v[150:151] op_sel_hi:[1,0]
	v_rcp_f32_e32 v124, v114
	v_add_f32_e32 v115, 1.0, v115
	v_add_f32_e32 v116, 1.0, v116
	v_exp_f32_e32 v118, v118
	v_exp_f32_e32 v114, v119
	v_rcp_f32_e32 v119, v115
	v_mov_b32_e32 v115, v120
	v_rcp_f32_e32 v120, v116
	v_exp_f32_e32 v115, v115
	v_exp_f32_e32 v116, v121
	v_exp_f32_e32 v117, v117
	v_add_f32_e32 v118, 1.0, v118
	v_add_f32_e32 v114, 1.0, v114
	v_pk_mul_f32 v[106:107], v[106:107], v[148:149] op_sel_hi:[1,0]
	v_rcp_f32_e32 v118, v118
	v_rcp_f32_e32 v114, v114
	v_add_f32_e32 v115, 1.0, v115
	v_add_f32_e32 v116, 1.0, v116
	v_add_f32_e32 v117, 1.0, v117
	v_pk_mul_f32 v[108:109], v[108:109], v[148:149] op_sel_hi:[1,0]
	v_rcp_f32_e32 v115, v115
	v_rcp_f32_e32 v116, v116
	v_rcp_f32_e32 v117, v117
	v_exp_f32_e32 v106, v106
	v_exp_f32_e32 v107, v107
	v_exp_f32_e32 v108, v108
	v_cvt_pk_bf16_f32 v114, v118, v114
	v_add_co_u32_e32 v118, vcc, s0, v122
	v_cvt_pk_bf16_f32 v115, v115, v116
	v_cvt_pk_bf16_f32 v116, v124, v119
	v_cvt_pk_bf16_f32 v117, v120, v117
	v_addc_co_u32_e32 v119, vcc, 0, v123, vcc
	v_pk_mul_f32 v[110:111], v[110:111], v[148:149] op_sel_hi:[1,0]
	v_add_f32_e32 v106, 1.0, v106
	global_store_dwordx4 v[118:119], v[114:117], off
	v_pk_mul_f32 v[112:113], v[112:113], v[148:149] op_sel_hi:[1,0]
	v_rcp_f32_e32 v114, v106
	v_add_f32_e32 v107, 1.0, v107
	v_add_f32_e32 v108, 1.0, v108
	v_exp_f32_e32 v110, v110
	v_exp_f32_e32 v106, v111
	v_rcp_f32_e32 v111, v107
	v_mov_b32_e32 v107, v112
	v_rcp_f32_e32 v112, v108
	v_add_f32_e32 v142, v142, v143
	v_exp_f32_e32 v107, v107
	v_exp_f32_e32 v108, v113
	v_exp_f32_e32 v109, v109
	ds_swizzle_b32 v143, v142 offset:swizzle(SWAP,16)
	v_add_f32_e32 v110, 1.0, v110
	v_add_f32_e32 v106, 1.0, v106
	v_pk_mul_f32 v[98:99], v[98:99], v[148:149] op_sel_hi:[1,0]
	v_rcp_f32_e32 v110, v110
	v_rcp_f32_e32 v106, v106
	v_add_f32_e32 v107, 1.0, v107
	v_add_f32_e32 v108, 1.0, v108
	v_add_f32_e32 v109, 1.0, v109
	v_pk_mul_f32 v[100:101], v[100:101], v[148:149] op_sel_hi:[1,0]
	v_rcp_f32_e32 v107, v107
	v_rcp_f32_e32 v108, v108
	v_rcp_f32_e32 v109, v109
	v_exp_f32_e32 v98, v98
	s_waitcnt lgkmcnt(0)
	v_add_f32_e32 v142, v142, v143
	v_exp_f32_e32 v99, v99
	v_exp_f32_e32 v100, v100
	v_mov_b32_e32 v143, v142
	s_nop 1
	v_permlane32_swap_b32_e32 v142, v143
	v_cvt_pk_bf16_f32 v106, v110, v106
	v_add_co_u32_e32 v110, vcc, s1, v122
	v_add_f32_e32 v142, v142, v143
	v_cvt_pk_bf16_f32 v107, v107, v108
	v_cvt_pk_bf16_f32 v108, v114, v111
	v_cvt_pk_bf16_f32 v109, v112, v109
	v_addc_co_u32_e32 v111, vcc, 0, v123, vcc
	v_pk_mul_f32 v[102:103], v[102:103], v[148:149] op_sel_hi:[1,0]
	v_add_f32_e32 v98, 1.0, v98
	v_fmamk_f32 v142, v142, 0x3a800000, v254
	global_store_dwordx4 v[110:111], v[106:109], off
	v_pk_mul_f32 v[104:105], v[104:105], v[148:149] op_sel_hi:[1,0]
	v_rcp_f32_e32 v106, v98
	v_add_f32_e32 v99, 1.0, v99
	v_add_f32_e32 v100, 1.0, v100
	v_rsq_f32_e32 v146, v142
	s_nop 0
	v_mul_f32_e32 v146, 0xbfb8aa3b, v146
	v_exp_f32_e32 v102, v102
	v_exp_f32_e32 v98, v103
	v_rcp_f32_e32 v103, v99
	v_mov_b32_e32 v99, v104
	v_rcp_f32_e32 v104, v100
	v_exp_f32_e32 v99, v99
	v_exp_f32_e32 v100, v105
	v_exp_f32_e32 v101, v101
	v_add_f32_e32 v102, 1.0, v102
	v_add_f32_e32 v98, 1.0, v98
	v_pk_mul_f32 v[90:91], v[90:91], v[146:147] op_sel_hi:[1,0]
	v_rcp_f32_e32 v102, v102
	v_rcp_f32_e32 v98, v98
	v_add_f32_e32 v99, 1.0, v99
	v_add_f32_e32 v100, 1.0, v100
	v_add_f32_e32 v101, 1.0, v101
	v_pk_mul_f32 v[92:93], v[92:93], v[146:147] op_sel_hi:[1,0]
	v_rcp_f32_e32 v99, v99
	v_rcp_f32_e32 v100, v100
	v_rcp_f32_e32 v101, v101
	v_exp_f32_e32 v90, v90
	v_exp_f32_e32 v91, v91
	v_exp_f32_e32 v92, v92
	s_mov_b32 s0, 0xa000
	v_cvt_pk_bf16_f32 v98, v102, v98
	v_add_co_u32_e32 v102, vcc, s0, v122
	v_cvt_pk_bf16_f32 v99, v99, v100
	v_cvt_pk_bf16_f32 v100, v106, v103
	v_cvt_pk_bf16_f32 v101, v104, v101
	v_addc_co_u32_e32 v103, vcc, 0, v123, vcc
	v_pk_mul_f32 v[94:95], v[94:95], v[146:147] op_sel_hi:[1,0]
	v_add_f32_e32 v90, 1.0, v90
	v_mov_b32_e32 v142, v157
	v_mov_b32_e32 v143, v158
	v_mov_b32_e32 v157, v159
	global_store_dwordx4 v[102:103], v[98:101], off
	v_pk_mul_f32 v[96:97], v[96:97], v[146:147] op_sel_hi:[1,0]
	v_rcp_f32_e32 v98, v90
	v_add_f32_e32 v91, 1.0, v91
	v_add_f32_e32 v92, 1.0, v92
	v_pk_add_f32 v[142:143], v[142:143], v[156:157]
	v_exp_f32_e32 v94, v94
	v_exp_f32_e32 v90, v95
	v_rcp_f32_e32 v95, v91
	v_mov_b32_e32 v91, v96
	v_rcp_f32_e32 v96, v92
	v_add_f32_e32 v142, v142, v143
	v_exp_f32_e32 v91, v91
	v_exp_f32_e32 v92, v97
	v_exp_f32_e32 v93, v93
	ds_swizzle_b32 v143, v142 offset:swizzle(SWAP,16)
	v_add_f32_e32 v94, 1.0, v94
	v_add_f32_e32 v90, 1.0, v90
	v_pk_mul_f32 v[82:83], v[82:83], v[146:147] op_sel_hi:[1,0]
	v_rcp_f32_e32 v94, v94
	v_rcp_f32_e32 v90, v90
	v_add_f32_e32 v91, 1.0, v91
	v_add_f32_e32 v92, 1.0, v92
	v_add_f32_e32 v93, 1.0, v93
	v_pk_mul_f32 v[84:85], v[84:85], v[146:147] op_sel_hi:[1,0]
	v_rcp_f32_e32 v91, v91
	v_rcp_f32_e32 v92, v92
	v_rcp_f32_e32 v93, v93
	v_exp_f32_e32 v82, v82
	s_waitcnt lgkmcnt(0)
	v_add_f32_e32 v142, v142, v143
	v_exp_f32_e32 v83, v83
	v_exp_f32_e32 v84, v84
	v_mov_b32_e32 v143, v142
	s_movk_i32 s0, 0x4000
	s_nop 0
	v_permlane32_swap_b32_e32 v142, v143
	v_cvt_pk_bf16_f32 v90, v94, v90
	v_add_co_u32_e32 v94, vcc, s0, v122
	v_add_f32_e32 v142, v142, v143
	v_cvt_pk_bf16_f32 v91, v91, v92
	v_cvt_pk_bf16_f32 v92, v98, v95
	v_cvt_pk_bf16_f32 v93, v96, v93
	v_addc_co_u32_e32 v95, vcc, 0, v123, vcc
	v_pk_mul_f32 v[86:87], v[86:87], v[146:147] op_sel_hi:[1,0]
	v_add_f32_e32 v82, 1.0, v82
	v_fmamk_f32 v142, v142, 0x3a800000, v254
	global_store_dwordx4 v[94:95], v[90:93], off
	v_pk_mul_f32 v[88:89], v[88:89], v[146:147] op_sel_hi:[1,0]
	v_rcp_f32_e32 v90, v82
	v_add_f32_e32 v83, 1.0, v83
	v_add_f32_e32 v84, 1.0, v84
	v_rsq_f32_e32 v144, v142
	s_nop 0
	v_mul_f32_e32 v144, 0xbfb8aa3b, v144
	v_exp_f32_e32 v86, v86
	v_exp_f32_e32 v82, v87
	v_rcp_f32_e32 v87, v83
	v_mov_b32_e32 v83, v88
	v_rcp_f32_e32 v88, v84
	v_exp_f32_e32 v83, v83
	v_exp_f32_e32 v84, v89
	v_exp_f32_e32 v85, v85
	v_add_f32_e32 v86, 1.0, v86
	v_add_f32_e32 v82, 1.0, v82
	v_pk_mul_f32 v[74:75], v[74:75], v[144:145] op_sel_hi:[1,0]
	v_rcp_f32_e32 v86, v86
	v_rcp_f32_e32 v82, v82
	v_add_f32_e32 v83, 1.0, v83
	v_add_f32_e32 v84, 1.0, v84
	v_add_f32_e32 v85, 1.0, v85
	v_pk_mul_f32 v[76:77], v[76:77], v[144:145] op_sel_hi:[1,0]
	v_rcp_f32_e32 v83, v83
	v_rcp_f32_e32 v84, v84
	v_rcp_f32_e32 v85, v85
	v_exp_f32_e32 v74, v74
	v_exp_f32_e32 v75, v75
	v_exp_f32_e32 v76, v76
	s_mov_b32 s0, 0xc000
	v_cvt_pk_bf16_f32 v82, v86, v82
	v_add_co_u32_e32 v86, vcc, s0, v122
	v_cvt_pk_bf16_f32 v83, v83, v84
	v_cvt_pk_bf16_f32 v84, v90, v87
	v_cvt_pk_bf16_f32 v85, v88, v85
	v_addc_co_u32_e32 v87, vcc, 0, v123, vcc
	v_pk_mul_f32 v[78:79], v[78:79], v[144:145] op_sel_hi:[1,0]
	v_add_f32_e32 v74, 1.0, v74
	v_mov_b32_e32 v142, v161
	v_mov_b32_e32 v143, v162
	v_mov_b32_e32 v161, v163
	global_store_dwordx4 v[86:87], v[82:85], off
	v_pk_mul_f32 v[80:81], v[80:81], v[144:145] op_sel_hi:[1,0]
	v_rcp_f32_e32 v82, v74
	v_add_f32_e32 v75, 1.0, v75
	v_add_f32_e32 v76, 1.0, v76
	v_pk_add_f32 v[142:143], v[142:143], v[160:161]
	v_exp_f32_e32 v78, v78
	v_exp_f32_e32 v74, v79
	v_rcp_f32_e32 v79, v75
	v_mov_b32_e32 v75, v80
	v_rcp_f32_e32 v80, v76
	v_add_f32_e32 v142, v142, v143
	v_exp_f32_e32 v75, v75
	v_exp_f32_e32 v76, v81
	v_exp_f32_e32 v77, v77
	ds_swizzle_b32 v143, v142 offset:swizzle(SWAP,16)
	v_add_f32_e32 v78, 1.0, v78
	v_add_f32_e32 v74, 1.0, v74
	v_pk_mul_f32 v[66:67], v[66:67], v[144:145] op_sel_hi:[1,0]
	v_rcp_f32_e32 v78, v78
	v_rcp_f32_e32 v74, v74
	v_add_f32_e32 v75, 1.0, v75
	v_add_f32_e32 v76, 1.0, v76
	v_add_f32_e32 v77, 1.0, v77
	v_pk_mul_f32 v[68:69], v[68:69], v[144:145] op_sel_hi:[1,0]
	v_rcp_f32_e32 v75, v75
	v_rcp_f32_e32 v76, v76
	v_rcp_f32_e32 v77, v77
	v_exp_f32_e32 v66, v66
	s_waitcnt lgkmcnt(0)
	v_add_f32_e32 v142, v142, v143
	v_exp_f32_e32 v67, v67
	v_exp_f32_e32 v68, v68
	v_mov_b32_e32 v143, v142
	s_movk_i32 s0, 0x6000
	s_nop 0
	v_permlane32_swap_b32_e32 v142, v143
	v_cvt_pk_bf16_f32 v74, v78, v74
	v_add_co_u32_e32 v78, vcc, s0, v122
	v_add_f32_e32 v142, v142, v143
	v_cvt_pk_bf16_f32 v75, v75, v76
	v_cvt_pk_bf16_f32 v76, v82, v79
	v_cvt_pk_bf16_f32 v77, v80, v77
	v_addc_co_u32_e32 v79, vcc, 0, v123, vcc
	v_pk_mul_f32 v[70:71], v[70:71], v[144:145] op_sel_hi:[1,0]
	v_add_f32_e32 v66, 1.0, v66
	v_fmamk_f32 v142, v142, 0x3a800000, v254
	global_store_dwordx4 v[78:79], v[74:77], off
	v_pk_mul_f32 v[72:73], v[72:73], v[144:145] op_sel_hi:[1,0]
	v_rcp_f32_e32 v74, v66
	v_add_f32_e32 v67, 1.0, v67
	v_add_f32_e32 v68, 1.0, v68
	v_rsq_f32_e32 v142, v142
	s_nop 0
	v_mul_f32_e32 v142, 0xbfb8aa3b, v142
	v_exp_f32_e32 v70, v70
	v_exp_f32_e32 v66, v71
	v_rcp_f32_e32 v71, v67
	v_mov_b32_e32 v67, v72
	v_rcp_f32_e32 v72, v68
	v_exp_f32_e32 v67, v67
	v_exp_f32_e32 v68, v73
	v_exp_f32_e32 v69, v69
	v_add_f32_e32 v70, 1.0, v70
	v_add_f32_e32 v66, 1.0, v66
	v_pk_mul_f32 v[58:59], v[58:59], v[142:143] op_sel_hi:[1,0]
	v_rcp_f32_e32 v70, v70
	v_rcp_f32_e32 v66, v66
	v_add_f32_e32 v67, 1.0, v67
	v_add_f32_e32 v68, 1.0, v68
	v_add_f32_e32 v69, 1.0, v69
	v_pk_mul_f32 v[60:61], v[60:61], v[142:143] op_sel_hi:[1,0]
	v_rcp_f32_e32 v67, v67
	v_rcp_f32_e32 v68, v68
	v_rcp_f32_e32 v69, v69
	v_exp_f32_e32 v58, v58
	v_exp_f32_e32 v59, v59
	v_exp_f32_e32 v60, v60
	s_mov_b32 s0, 0xe000
	v_cvt_pk_bf16_f32 v66, v70, v66
	v_add_co_u32_e32 v70, vcc, s0, v122
	v_cvt_pk_bf16_f32 v67, v67, v68
	v_cvt_pk_bf16_f32 v68, v74, v71
	v_cvt_pk_bf16_f32 v69, v72, v69
	v_addc_co_u32_e32 v71, vcc, 0, v123, vcc
	v_pk_mul_f32 v[62:63], v[62:63], v[142:143] op_sel_hi:[1,0]
	v_add_f32_e32 v58, 1.0, v58
	global_store_dwordx4 v[70:71], v[66:69], off
	v_pk_mul_f32 v[64:65], v[64:65], v[142:143] op_sel_hi:[1,0]
	v_rcp_f32_e32 v66, v58
	v_add_f32_e32 v59, 1.0, v59
	v_add_f32_e32 v60, 1.0, v60
	v_pk_add_f32 v[138:139], v[152:153], v[138:139]
	v_exp_f32_e32 v62, v62
	v_exp_f32_e32 v58, v63
	v_rcp_f32_e32 v63, v59
	v_mov_b32_e32 v59, v64
	v_rcp_f32_e32 v64, v60
	v_add_f32_e32 v138, v138, v139
	v_exp_f32_e32 v59, v59
	v_exp_f32_e32 v60, v65
	v_exp_f32_e32 v61, v61
	ds_swizzle_b32 v139, v138 offset:swizzle(SWAP,16)
	v_add_f32_e32 v62, 1.0, v62
	v_add_f32_e32 v58, 1.0, v58
	v_pk_mul_f32 v[50:51], v[50:51], v[142:143] op_sel_hi:[1,0]
	v_rcp_f32_e32 v62, v62
	v_rcp_f32_e32 v58, v58
	v_add_f32_e32 v59, 1.0, v59
	v_add_f32_e32 v60, 1.0, v60
	v_add_f32_e32 v61, 1.0, v61
	v_pk_mul_f32 v[52:53], v[52:53], v[142:143] op_sel_hi:[1,0]
	v_rcp_f32_e32 v59, v59
	v_rcp_f32_e32 v60, v60
	v_rcp_f32_e32 v61, v61
	v_exp_f32_e32 v50, v50
	s_waitcnt lgkmcnt(0)
	v_add_f32_e32 v138, v138, v139
	v_exp_f32_e32 v51, v51
	v_exp_f32_e32 v52, v52
	v_mov_b32_e32 v139, v138
	s_nop 1
	v_permlane32_swap_b32_e32 v138, v139
	v_cvt_pk_bf16_f32 v58, v62, v58
	v_add_co_u32_e32 v62, vcc, s97, v122
	v_add_f32_e32 v138, v138, v139
	v_cvt_pk_bf16_f32 v59, v59, v60
	v_cvt_pk_bf16_f32 v60, v66, v63
	v_cvt_pk_bf16_f32 v61, v64, v61
	v_addc_co_u32_e32 v63, vcc, 0, v123, vcc
	v_pk_mul_f32 v[54:55], v[54:55], v[142:143] op_sel_hi:[1,0]
	v_add_f32_e32 v50, 1.0, v50
	v_fmamk_f32 v138, v138, 0x3a800000, v254
	global_store_dwordx4 v[62:63], v[58:61], off
	v_pk_mul_f32 v[56:57], v[56:57], v[142:143] op_sel_hi:[1,0]
	v_rcp_f32_e32 v58, v50
	v_add_f32_e32 v51, 1.0, v51
	v_add_f32_e32 v52, 1.0, v52
	v_rsq_f32_e32 v138, v138
	s_nop 0
	v_mul_f32_e32 v138, 0xbfb8aa3b, v138
	v_exp_f32_e32 v54, v54
	v_exp_f32_e32 v50, v55
	v_rcp_f32_e32 v55, v51
	v_mov_b32_e32 v51, v56
	v_rcp_f32_e32 v56, v52
	v_exp_f32_e32 v51, v51
	v_exp_f32_e32 v52, v57
	v_exp_f32_e32 v53, v53
	v_add_f32_e32 v54, 1.0, v54
	v_add_f32_e32 v50, 1.0, v50
	v_pk_mul_f32 v[42:43], v[42:43], v[138:139] op_sel_hi:[1,0]
	v_rcp_f32_e32 v54, v54
	v_rcp_f32_e32 v50, v50
	v_add_f32_e32 v51, 1.0, v51
	v_add_f32_e32 v52, 1.0, v52
	v_add_f32_e32 v53, 1.0, v53
	v_pk_mul_f32 v[44:45], v[44:45], v[138:139] op_sel_hi:[1,0]
	v_rcp_f32_e32 v51, v51
	v_rcp_f32_e32 v52, v52
	v_rcp_f32_e32 v53, v53
	v_exp_f32_e32 v42, v42
	v_exp_f32_e32 v43, v43
	v_exp_f32_e32 v44, v44
	s_mov_b32 s0, 0x18000
	v_cvt_pk_bf16_f32 v50, v54, v50
	v_add_co_u32_e32 v54, vcc, s0, v122
	v_cvt_pk_bf16_f32 v51, v51, v52
	v_cvt_pk_bf16_f32 v52, v58, v55
	v_cvt_pk_bf16_f32 v53, v56, v53
	v_addc_co_u32_e32 v55, vcc, 0, v123, vcc
	v_pk_mul_f32 v[46:47], v[46:47], v[138:139] op_sel_hi:[1,0]
	v_add_f32_e32 v42, 1.0, v42
	global_store_dwordx4 v[54:55], v[50:53], off
	v_pk_mul_f32 v[48:49], v[48:49], v[138:139] op_sel_hi:[1,0]
	v_rcp_f32_e32 v50, v42
	v_add_f32_e32 v43, 1.0, v43
	v_add_f32_e32 v44, 1.0, v44
	v_pk_add_f32 v[134:135], v[140:141], v[134:135]
	v_exp_f32_e32 v46, v46
	v_exp_f32_e32 v42, v47
	v_rcp_f32_e32 v47, v43
	v_mov_b32_e32 v43, v48
	v_rcp_f32_e32 v48, v44
	v_add_f32_e32 v134, v134, v135
	v_exp_f32_e32 v43, v43
	v_exp_f32_e32 v44, v49
	v_exp_f32_e32 v45, v45
	ds_swizzle_b32 v135, v134 offset:swizzle(SWAP,16)
	v_add_f32_e32 v46, 1.0, v46
	v_add_f32_e32 v42, 1.0, v42
	v_pk_mul_f32 v[34:35], v[34:35], v[138:139] op_sel_hi:[1,0]
	v_rcp_f32_e32 v46, v46
	v_rcp_f32_e32 v42, v42
	v_add_f32_e32 v43, 1.0, v43
	v_add_f32_e32 v44, 1.0, v44
	v_add_f32_e32 v45, 1.0, v45
	v_pk_mul_f32 v[36:37], v[36:37], v[138:139] op_sel_hi:[1,0]
	v_rcp_f32_e32 v43, v43
	v_rcp_f32_e32 v44, v44
	v_rcp_f32_e32 v45, v45
	v_exp_f32_e32 v34, v34
	s_waitcnt lgkmcnt(0)
	v_add_f32_e32 v134, v134, v135
	v_exp_f32_e32 v35, v35
	v_exp_f32_e32 v36, v36
	v_mov_b32_e32 v135, v134
	s_mov_b32 s0, 0x12000
	s_nop 0
	v_permlane32_swap_b32_e32 v134, v135
	v_cvt_pk_bf16_f32 v42, v46, v42
	v_add_co_u32_e32 v46, vcc, s0, v122
	v_add_f32_e32 v134, v134, v135
	v_cvt_pk_bf16_f32 v43, v43, v44
	v_cvt_pk_bf16_f32 v44, v50, v47
	v_cvt_pk_bf16_f32 v45, v48, v45
	v_addc_co_u32_e32 v47, vcc, 0, v123, vcc
	v_pk_mul_f32 v[38:39], v[38:39], v[138:139] op_sel_hi:[1,0]
	v_add_f32_e32 v34, 1.0, v34
	v_fmamk_f32 v134, v134, 0x3a800000, v254
	global_store_dwordx4 v[46:47], v[42:45], off
	v_pk_mul_f32 v[40:41], v[40:41], v[138:139] op_sel_hi:[1,0]
	v_rcp_f32_e32 v42, v34
	v_add_f32_e32 v35, 1.0, v35
	v_add_f32_e32 v36, 1.0, v36
	v_rsq_f32_e32 v134, v134
	s_nop 0
	v_mul_f32_e32 v134, 0xbfb8aa3b, v134
	v_exp_f32_e32 v38, v38
	v_exp_f32_e32 v34, v39
	v_rcp_f32_e32 v39, v35
	v_mov_b32_e32 v35, v40
	v_rcp_f32_e32 v40, v36
	v_exp_f32_e32 v35, v35
	v_exp_f32_e32 v36, v41
	v_exp_f32_e32 v37, v37
	v_add_f32_e32 v38, 1.0, v38
	v_add_f32_e32 v34, 1.0, v34
	v_pk_mul_f32 v[26:27], v[26:27], v[134:135] op_sel_hi:[1,0]
	v_rcp_f32_e32 v38, v38
	v_rcp_f32_e32 v34, v34
	v_add_f32_e32 v35, 1.0, v35
	v_add_f32_e32 v36, 1.0, v36
	v_add_f32_e32 v37, 1.0, v37
	v_pk_mul_f32 v[28:29], v[28:29], v[134:135] op_sel_hi:[1,0]
	v_rcp_f32_e32 v35, v35
	v_rcp_f32_e32 v36, v36
	v_rcp_f32_e32 v37, v37
	v_exp_f32_e32 v26, v26
	v_exp_f32_e32 v27, v27
	v_exp_f32_e32 v28, v28
	s_mov_b32 s0, 0x1a000
	v_cvt_pk_bf16_f32 v34, v38, v34
	v_add_co_u32_e32 v38, vcc, s0, v122
	v_cvt_pk_bf16_f32 v35, v35, v36
	v_cvt_pk_bf16_f32 v36, v42, v39
	v_cvt_pk_bf16_f32 v37, v40, v37
	v_addc_co_u32_e32 v39, vcc, 0, v123, vcc
	v_pk_mul_f32 v[30:31], v[30:31], v[134:135] op_sel_hi:[1,0]
	v_add_f32_e32 v26, 1.0, v26
	global_store_dwordx4 v[38:39], v[34:37], off
	v_pk_mul_f32 v[32:33], v[32:33], v[134:135] op_sel_hi:[1,0]
	v_rcp_f32_e32 v34, v26
	v_add_f32_e32 v27, 1.0, v27
	v_add_f32_e32 v28, 1.0, v28
	v_exp_f32_e32 v30, v30
	v_exp_f32_e32 v26, v31
	v_rcp_f32_e32 v31, v27
	v_mov_b32_e32 v27, v32
	v_rcp_f32_e32 v32, v28
	v_exp_f32_e32 v27, v27
	v_exp_f32_e32 v28, v33
	v_exp_f32_e32 v29, v29
	v_add_f32_e32 v30, 1.0, v30
	v_add_f32_e32 v26, 1.0, v26
	v_pk_mul_f32 v[18:19], v[18:19], v[134:135] op_sel_hi:[1,0]
	v_rcp_f32_e32 v30, v30
	v_rcp_f32_e32 v26, v26
	v_add_f32_e32 v27, 1.0, v27
	v_add_f32_e32 v28, 1.0, v28
	v_add_f32_e32 v29, 1.0, v29
	v_pk_mul_f32 v[20:21], v[20:21], v[134:135] op_sel_hi:[1,0]
	v_rcp_f32_e32 v27, v27
	v_rcp_f32_e32 v28, v28
	v_rcp_f32_e32 v29, v29
	v_exp_f32_e32 v18, v18
	v_exp_f32_e32 v19, v19
	v_exp_f32_e32 v20, v20
	s_mov_b32 s0, 0x14000
	v_cvt_pk_bf16_f32 v26, v30, v26
	v_add_co_u32_e32 v30, vcc, s0, v122
	v_cvt_pk_bf16_f32 v27, v27, v28
	v_cvt_pk_bf16_f32 v28, v34, v31
	v_cvt_pk_bf16_f32 v29, v32, v29
	v_addc_co_u32_e32 v31, vcc, 0, v123, vcc
	v_pk_mul_f32 v[22:23], v[22:23], v[134:135] op_sel_hi:[1,0]
	v_add_f32_e32 v18, 1.0, v18
	v_fmamk_f32 v130, v130, 0x3a800000, v254
	global_store_dwordx4 v[30:31], v[26:29], off
	v_pk_mul_f32 v[24:25], v[24:25], v[134:135] op_sel_hi:[1,0]
	v_rcp_f32_e32 v26, v18
	v_add_f32_e32 v19, 1.0, v19
	v_add_f32_e32 v20, 1.0, v20
	v_rsq_f32_e32 v130, v130
	s_nop 0
	v_mul_f32_e32 v130, 0xbfb8aa3b, v130
	v_exp_f32_e32 v22, v22
	v_exp_f32_e32 v18, v23
	v_rcp_f32_e32 v23, v19
	v_mov_b32_e32 v19, v24
	v_rcp_f32_e32 v24, v20
	v_exp_f32_e32 v19, v19
	v_exp_f32_e32 v20, v25
	v_exp_f32_e32 v21, v21
	v_add_f32_e32 v22, 1.0, v22
	v_add_f32_e32 v18, 1.0, v18
	v_pk_mul_f32 v[10:11], v[10:11], v[130:131] op_sel_hi:[1,0]
	v_rcp_f32_e32 v22, v22
	v_rcp_f32_e32 v18, v18
	v_add_f32_e32 v19, 1.0, v19
	v_add_f32_e32 v20, 1.0, v20
	v_add_f32_e32 v21, 1.0, v21
	v_pk_mul_f32 v[12:13], v[12:13], v[130:131] op_sel_hi:[1,0]
	v_rcp_f32_e32 v19, v19
	v_rcp_f32_e32 v20, v20
	v_rcp_f32_e32 v21, v21
	v_exp_f32_e32 v10, v10
	v_exp_f32_e32 v11, v11
	v_exp_f32_e32 v12, v12
	s_mov_b32 s0, 0x1c000
	v_cvt_pk_bf16_f32 v18, v22, v18
	v_add_co_u32_e32 v22, vcc, s0, v122
	v_cvt_pk_bf16_f32 v19, v19, v20
	v_cvt_pk_bf16_f32 v20, v26, v23
	v_cvt_pk_bf16_f32 v21, v24, v21
	v_addc_co_u32_e32 v23, vcc, 0, v123, vcc
	v_pk_mul_f32 v[14:15], v[14:15], v[130:131] op_sel_hi:[1,0]
	v_add_f32_e32 v10, 1.0, v10
	global_store_dwordx4 v[22:23], v[18:21], off
	v_pk_mul_f32 v[16:17], v[16:17], v[130:131] op_sel_hi:[1,0]
	v_rcp_f32_e32 v18, v10
	v_add_f32_e32 v11, 1.0, v11
	v_add_f32_e32 v12, 1.0, v12
	v_exp_f32_e32 v14, v14
	v_exp_f32_e32 v10, v15
	v_rcp_f32_e32 v15, v11
	v_mov_b32_e32 v11, v16
	v_rcp_f32_e32 v16, v12
	v_exp_f32_e32 v11, v11
	v_exp_f32_e32 v12, v17
	v_exp_f32_e32 v13, v13
	v_add_f32_e32 v14, 1.0, v14
	v_add_f32_e32 v10, 1.0, v10
	v_pk_mul_f32 v[2:3], v[2:3], v[130:131] op_sel_hi:[1,0]
	v_rcp_f32_e32 v14, v14
	v_rcp_f32_e32 v10, v10
	v_add_f32_e32 v11, 1.0, v11
	v_add_f32_e32 v12, 1.0, v12
	v_add_f32_e32 v13, 1.0, v13
	v_pk_mul_f32 v[4:5], v[4:5], v[130:131] op_sel_hi:[1,0]
	v_rcp_f32_e32 v11, v11
	v_rcp_f32_e32 v12, v12
	v_rcp_f32_e32 v13, v13
	v_exp_f32_e32 v2, v2
	v_exp_f32_e32 v3, v3
	v_exp_f32_e32 v4, v4
	s_mov_b32 s0, 0x16000
	v_cvt_pk_bf16_f32 v10, v14, v10
	v_add_co_u32_e32 v14, vcc, s0, v122
	v_cvt_pk_bf16_f32 v11, v11, v12
	v_cvt_pk_bf16_f32 v12, v18, v15
	v_cvt_pk_bf16_f32 v13, v16, v13
	v_addc_co_u32_e32 v15, vcc, 0, v123, vcc
	v_pk_mul_f32 v[6:7], v[6:7], v[130:131] op_sel_hi:[1,0]
	v_add_f32_e32 v2, 1.0, v2
	global_store_dwordx4 v[14:15], v[10:13], off
	v_pk_mul_f32 v[8:9], v[8:9], v[130:131] op_sel_hi:[1,0]
	v_rcp_f32_e32 v10, v2
	v_add_f32_e32 v3, 1.0, v3
	v_add_f32_e32 v4, 1.0, v4
	v_exp_f32_e32 v6, v6
	v_exp_f32_e32 v2, v7
	v_rcp_f32_e32 v7, v3
	v_mov_b32_e32 v3, v8
	v_rcp_f32_e32 v8, v4
	v_exp_f32_e32 v3, v3
	v_exp_f32_e32 v4, v9
	v_exp_f32_e32 v5, v5
	v_add_f32_e32 v6, 1.0, v6
	v_add_f32_e32 v2, 1.0, v2
	v_rcp_f32_e32 v6, v6
	v_rcp_f32_e32 v2, v2
	v_add_f32_e32 v3, 1.0, v3
	v_add_f32_e32 v4, 1.0, v4
	v_add_f32_e32 v5, 1.0, v5
	v_rcp_f32_e32 v3, v3
	v_rcp_f32_e32 v4, v4
	v_rcp_f32_e32 v5, v5
	v_cvt_pk_bf16_f32 v2, v6, v2
	v_add_co_u32_e32 v6, vcc, 0x1e000, v122
	v_cvt_pk_bf16_f32 v3, v3, v4
	v_cvt_pk_bf16_f32 v4, v10, v7
	v_cvt_pk_bf16_f32 v5, v8, v5
	v_addc_co_u32_e32 v7, vcc, 0, v123, vcc
	global_store_dwordx4 v[6:7], v[2:5], off
	s_andn2_b64 vcc, exec, s[20:21]
	s_mov_b64 s[0:1], -1
	s_cbranch_vccnz .LBB0_1125
